# v112 + attention: common tile path duplicated per K/V buffer parity so fragment addresses are per-unit bases plus DS immediates (ten v_add_u32 per key tile removed; generic address registers rebuilt o
# speedup vs baseline: 1.0050x; 1.0050x over previous
; __device__ __forceinline__ void apply_mask(bool MASK, f32x16& s0, int kvr, int r, int h) {
;     if (MASK) {
;         asm volatile("" ::: "memory");
;         const int d = r - 4 * h - kvr;
; #pragma unroll
;         for (int i = 0; i < 16; ++i) { if (((i & 3) + 8 * (i >> 2)) > d) s0[i] = -INFINITY; }
;     }
; }
.Lhead_mask_p0:
	v_cmp_gt_i32_e32 vcc, 26, v214
	v_cmp_gt_i32_e64 s[34:35], 25, v214
	v_cmp_gt_i32_e64 s[28:29], 24, v214
	s_and_b64 s[34:35], vcc, s[34:35]
	v_cmp_gt_i32_e64 s[26:27], 19, v214
	s_and_b64 s[28:29], s[34:35], s[28:29]
	v_cmp_gt_i32_e64 s[24:25], 18, v214
	s_and_b64 s[26:27], s[28:29], s[26:27]
	v_cmp_gt_i32_e64 s[22:23], 17, v214
	s_and_b64 s[24:25], s[26:27], s[24:25]
	v_cmp_gt_i32_e64 s[20:21], 16, v214
	s_and_b64 s[22:23], s[24:25], s[22:23]
	v_cmp_gt_i32_e64 s[18:19], 11, v214
	s_and_b64 s[20:21], s[22:23], s[20:21]
	v_cmp_gt_i32_e64 s[16:17], 10, v214
	s_and_b64 s[18:19], s[20:21], s[18:19]
	v_cmp_gt_i32_e64 s[14:15], 9, v214
	s_and_b64 s[16:17], s[18:19], s[16:17]
	v_cmp_gt_i32_e64 s[12:13], 8, v214
	s_and_b64 s[14:15], s[16:17], s[14:15]
	v_cmp_gt_i32_e64 s[10:11], 3, v214
	s_and_b64 s[12:13], s[14:15], s[12:13]
	v_cmp_gt_i32_e64 s[8:9], 2, v214
	s_and_b64 s[10:11], s[12:13], s[10:11]
	v_cmp_gt_i32_e64 s[6:7], 1, v214
	s_and_b64 s[8:9], s[10:11], s[8:9]
	v_cmp_gt_i32_e64 s[4:5], 0, v214
	s_and_b64 s[6:7], s[8:9], s[6:7]
	s_and_b64 s[4:5], s[6:7], s[4:5]
	v_cndmask_b32_e64 v183, v183, v17, s[34:35]
	v_cndmask_b32_e64 v182, v182, v17, s[28:29]
	v_cndmask_b32_e64 v181, v181, v17, s[26:27]
	v_cndmask_b32_e64 v180, v180, v17, s[24:25]
	v_cndmask_b32_e64 v179, v179, v17, s[22:23]
	v_cndmask_b32_e64 v178, v178, v17, s[20:21]
	v_cndmask_b32_e64 v177, v177, v17, s[18:19]
	v_cndmask_b32_e64 v176, v176, v17, s[16:17]
	v_cndmask_b32_e64 v175, v175, v17, s[14:15]
	v_cndmask_b32_e64 v174, v174, v17, s[12:13]
	v_cndmask_b32_e64 v173, v173, v17, s[10:11]
	v_cndmask_b32_e64 v172, v172, v17, s[8:9]
	v_cndmask_b32_e64 v171, v171, v17, s[6:7]
	v_cndmask_b32_e64 v170, v170, v17, s[4:5]
	v_cndmask_b32_e32 v184, v184, v17, vcc
	v_cmp_gt_i32_e32 vcc, 27, v214
	s_and_saveexec_b64 s[4:5], vcc
	v_mov_b32_e32 v185, s31
	s_or_b64 exec, exec, s[4:5]
	s_branch .LBB0_296_p0
.Ldisp_check_p1:
	v_or_b32_e32 v252, v0, v215
	v_cmp_eq_u32_e32 vcc, 0, v252
	s_cmp_eq_u64 vcc, exec
	s_cbranch_scc0 .Lfix_orig
	s_mov_b32 s101, 1
	s_branch .Lns_296_p1

; #define ATT_LAS __attribute__((address_space(3)))
; __device__ __forceinline__ int sub1(int a) { int v = a ^ 128; asm volatile("" : "+v"(v)); return v; }
; #define ATT_MFMA(a, b, c) __builtin_amdgcn_mfma_f32_32x32x16_bf16((a), (b), (c), 0, 0, 0)
; template <bool C1> __device__ __forceinline__ void qk_issue(f32x16& s0, const ATT_LAS unsigned char* kb, const ATT_LAS unsigned char* qb_, const int (&kaddr)[4]) {
; #pragma unroll
;     for (int i = 0; i < 16; ++i) s0[i] = 0.f;
; #pragma unroll
;     for (int ds = 0; ds < 4; ++ds) {
;         const int ad = C1 ? sub1(kaddr[ds]) : kaddr[ds];
;         const bf16x8 a0 = *(const ATT_LAS bf16x8*)(kb + ad);
;         const bf16x8 qv = *(const ATT_LAS bf16x8*)(qb_ + ad);
;         s0 = ATT_MFMA(a0, qv, s0);
;     }
; }
; __device__ __forceinline__ void tile_body(bool MASK, const ATT_LAS unsigned char* kb, const ATT_LAS unsigned char* vb, const ATT_LAS unsigned char* qbase, const int (&kaddr)[4], const int (&vaddr)[2], ...
;     ...
;     qk_issue<false>(Sa, kb, qbase, kaddr);
;     apply_mask(MASK, Sa, kvrel, r, h); ls = l1;
.LBB0_291:
	s_cmp_gt_i32 s80, 31
	s_cbranch_scc1 .Ldma_skip
	s_lshl_b32 s4, s4, 14
	s_add_i32 s81, s4, 0
	s_cmp_eq_u32 s81, 0
	s_cbranch_scc0 .Lpar1
	ds_read_b128 v[2:5], v203
	ds_read_b128 v[6:9], v217
	ds_read_b128 v[10:13], v204
	ds_read_b128 v[146:149], v219
	ds_read_b128 v[150:153], v205
	ds_read_b128 v[154:157], v221
	ds_read_b128 v[158:161], v206
	ds_read_b128 v[162:165], v223
	s_cmpk_gt_i32 s80, 0xffc1
	s_cselect_b64 s[36:37], -1, 0
	s_cmpk_lt_i32 s80, 0xffc2
	s_waitcnt lgkmcnt(4)
	v_mfma_f32_32x32x16_bf16 v[170:185], v[2:5], v[6:9], 0
	v_mfma_f32_32x32x16_bf16 v[170:185], v[10:13], v[146:149], v[170:185]
	s_waitcnt lgkmcnt(0)
	v_mfma_f32_32x32x16_bf16 v[170:185], v[150:153], v[154:157], v[170:185]
	v_mfma_f32_32x32x16_bf16 v[170:185], v[158:161], v[162:165], v[170:185]
	s_cbranch_scc0 .Lhead_mask_p0

; #define ATT_LAS __attribute__((address_space(3)))
; __device__ __forceinline__ unsigned cvtpk(float lo, float hi) { unsigned r; asm volatile("v_cvt_pk_bf16_f32 %0, %1, %2" : "=v"(r) : "v"(lo), "v"(hi)); return r; }
; template <bool HAS_PV, bool HAS_QK, bool C1> ...
;     s16x4 vlo[2], vhi[2]; bf16x8 ka, qa;
;     if (HAS_PV) {
; #pragma unroll
;         for (int u = 0; u < 2; ++u) { vlo[u] = vtr(vb + vaddr[0] + u * 512); vhi[u] = vtr(vb + vaddr[1] + u * 512); } }
;     if (HAS_QK) { const int ad = C1 ? sub1(kaddr[0]) : kaddr[0]; ka = *(const ATT_LAS bf16x8*)(kb + ad); qa = *(const ATT_LAS bf16x8*)(qb_ + ad);
; #pragma unroll
;         for (int i = 0; i < 16; ++i) Snext[i] = 0.f; }
;     float sa = 0.f, sb = 0.f;
; #pragma unroll
;     for (int g = 0; g < 4; ++g) {
;         s16x4 nlo[2], nhi[2]; bf16x8 nk, nq;
;         if (g < 3) {
;             if (HAS_PV) {
; #pragma unroll
;                 for (int u = 0; u < 2; ++u) { const int off = (2 * ((g + 1) & 1) + u) * 512 + ((g + 1) >> 1) * 4096; nlo[u] = vtr(vb + vaddr[0] + off); nhi[u] = vtr(vb + vaddr[1] + off); } }
;             if (HAS_QK) { const int ad = C1 ? sub1(kaddr[g + 1]) : kaddr[g + 1]; nk = *(const ATT_LAS bf16x8*)(kb + ad); nq = *(const ATT_LAS bf16x8*)(qb_ + ad); }
;         }
;         if (HAS_PV) { const bf16x8 pa = __builtin_bit_cast(bf16x8, pkin[g >> 1]);
; #pragma unroll
;             for (int u = 0; u < 2; ++u) { const bf16x8 vf = __builtin_shufflevector(vlo[u], vhi[u], 0, 1, 2, 3, 4, 5, 6, 7); Opv[2 * (g & 1) + u] = ATT_MFMA(pa, vf, Opv[2 * (g & 1) + u]); } }
;         if (HAS_QK) Snext = ATT_MFMA(ka, qa, Snext);
; #pragma unroll
;         for (int e = 4 * g; e < 4 * g + 4; e += 2) { Scur[e] = __builtin_amdgcn_exp2f(Scur[e] - m); Scur[e + 1] = __builtin_amdgcn_exp2f(Scur[e + 1] - m); sa += Scur[e]; sb += Scur[e + 1]; }
;         if (g & 1) pkout[g >> 1] = (u32x4){cvtpk(Scur[4 * g - 4], Scur[4 * g - 3]), cvtpk(Scur[4 * g - 2], Scur[4 * g - 1]), cvtpk(Scur[4 * g], Scur[4 * g + 1]), cvtpk(Scur[4 * g + 2], Scur[4 * g + 3])};
;         if (g < 3) {
;             if (HAS_PV) {
; #pragma unroll
;                 for (int u = 0; u < 2; ++u) { vlo[u] = nlo[u]; vhi[u] = nhi[u]; } }
;             if (HAS_QK) { ka = nk; qa = nq; }
;         }
;         __builtin_amdgcn_sched_barrier(0);
;     }
;     l += sa + sb;
;     return sa + sb;
; }
.Lns_296_p0:
	ds_read_b128 v[2:5], v209
	ds_read_b128 v[6:9], v244
	s_nop 1
	ds_read_b128 v[10:13], v210
	ds_read_b128 v[146:149], v245
	v_exp_f32_e32 v15, v170
	v_exp_f32_e32 v14, v171
	v_exp_f32_e32 v155, v172
	v_exp_f32_e32 v154, v173
	s_waitcnt lgkmcnt(2)
	v_mfma_f32_32x32x16_bf16 v[158:173], v[2:5], v[6:9], 0
	s_waitcnt lgkmcnt(0)
	v_mfma_f32_32x32x16_bf16 v[158:173], v[10:13], v[146:149], v[158:173]
	ds_read_b128 v[6:9], v211
	ds_read_b128 v[150:153], v246
	v_exp_f32_e32 v157, v174
	v_exp_f32_e32 v156, v175
	v_exp_f32_e32 v175, v176
	v_exp_f32_e32 v174, v177
	v_cvt_pk_bf16_f32 v2, v15, v14
	v_cvt_pk_bf16_f32 v3, v155, v154
	v_cvt_pk_bf16_f32 v4, v157, v156
	v_cvt_pk_bf16_f32 v5, v175, v174
	s_waitcnt lgkmcnt(0)
	v_mfma_f32_32x32x16_bf16 v[158:173], v[6:9], v[150:153], v[158:173]
	ds_read_b128 v[10:13], v212
	ds_read_b128 v[146:149], v247
	v_exp_f32_e32 v177, v178
	v_exp_f32_e32 v176, v179
	v_exp_f32_e32 v179, v180
	v_exp_f32_e32 v178, v181
	s_waitcnt lgkmcnt(0)
	v_mfma_f32_32x32x16_bf16 v[158:173], v[10:13], v[146:149], v[158:173]
	v_exp_f32_e32 v7, v182
	v_add_f32_e32 v14, v154, v14
	v_add_f32_e32 v15, v155, v15
	v_exp_f32_e32 v6, v183
	v_exp_f32_e32 v9, v184
	v_add_f32_e32 v14, v156, v14
	v_add_f32_e32 v15, v157, v15
	v_exp_f32_e32 v8, v185
	v_add_f32_e32 v14, v174, v14
	v_add_f32_e32 v15, v175, v15
	v_cvt_pk_bf16_f32 v10, v177, v176
	v_cvt_pk_bf16_f32 v11, v179, v178
	v_cvt_pk_bf16_f32 v12, v7, v6
	v_cvt_pk_bf16_f32 v13, v9, v8
	v_add_f32_e32 v14, v176, v14
	v_add_f32_e32 v15, v177, v15
	v_add_f32_e32 v14, v178, v14
	v_add_f32_e32 v15, v179, v15
	v_add_f32_e32 v6, v6, v14
	v_add_f32_e32 v7, v7, v15
	v_add_f32_e32 v6, v8, v6
	v_add_f32_e32 v7, v9, v7
	v_add_f32_e32 v6, v6, v7
	v_cmp_nge_f32_e32 vcc, s58, v6
	s_andn2_b64 s[4:5], exec, s[36:37]
	s_cbranch_vccnz .Lfix_slow_1

; #define ATT_LAS __attribute__((address_space(3)))
; __device__ __forceinline__ unsigned cvtpk(float lo, float hi) { unsigned r; asm volatile("v_cvt_pk_bf16_f32 %0, %1, %2" : "=v"(r) : "v"(lo), "v"(hi)); return r; }
; template <bool HAS_PV, bool HAS_QK, bool C1> ...
;     s16x4 vlo[2], vhi[2]; bf16x8 ka, qa;
;     if (HAS_PV) {
; #pragma unroll
;         for (int u = 0; u < 2; ++u) { vlo[u] = vtr(vb + vaddr[0] + u * 512); vhi[u] = vtr(vb + vaddr[1] + u * 512); } }
;     if (HAS_QK) { const int ad = C1 ? sub1(kaddr[0]) : kaddr[0]; ka = *(const ATT_LAS bf16x8*)(kb + ad); qa = *(const ATT_LAS bf16x8*)(qb_ + ad);
; #pragma unroll
;         for (int i = 0; i < 16; ++i) Snext[i] = 0.f; }
;     float sa = 0.f, sb = 0.f;
; #pragma unroll
;     for (int g = 0; g < 4; ++g) {
;         s16x4 nlo[2], nhi[2]; bf16x8 nk, nq;
;         if (g < 3) {
;             if (HAS_PV) {
; #pragma unroll
;                 for (int u = 0; u < 2; ++u) { const int off = (2 * ((g + 1) & 1) + u) * 512 + ((g + 1) >> 1) * 4096; nlo[u] = vtr(vb + vaddr[0] + off); nhi[u] = vtr(vb + vaddr[1] + off); } }
;             if (HAS_QK) { const int ad = C1 ? sub1(kaddr[g + 1]) : kaddr[g + 1]; nk = *(const ATT_LAS bf16x8*)(kb + ad); nq = *(const ATT_LAS bf16x8*)(qb_ + ad); }
;         }
;         if (HAS_PV) { const bf16x8 pa = __builtin_bit_cast(bf16x8, pkin[g >> 1]);
; #pragma unroll
;             for (int u = 0; u < 2; ++u) { const bf16x8 vf = __builtin_shufflevector(vlo[u], vhi[u], 0, 1, 2, 3, 4, 5, 6, 7); Opv[2 * (g & 1) + u] = ATT_MFMA(pa, vf, Opv[2 * (g & 1) + u]); } }
;         if (HAS_QK) Snext = ATT_MFMA(ka, qa, Snext);
; #pragma unroll
;         for (int e = 4 * g; e < 4 * g + 4; e += 2) { Scur[e] = __builtin_amdgcn_exp2f(Scur[e] - m); Scur[e + 1] = __builtin_amdgcn_exp2f(Scur[e + 1] - m); sa += Scur[e]; sb += Scur[e + 1]; }
;         if (g & 1) pkout[g >> 1] = (u32x4){cvtpk(Scur[4 * g - 4], Scur[4 * g - 3]), cvtpk(Scur[4 * g - 2], Scur[4 * g - 1]), cvtpk(Scur[4 * g], Scur[4 * g + 1]), cvtpk(Scur[4 * g + 2], Scur[4 * g + 3])};
;         if (g < 3) {
;             if (HAS_PV) {
; #pragma unroll
;                 for (int u = 0; u < 2; ++u) { vlo[u] = nlo[u]; vhi[u] = nhi[u]; } }
;             if (HAS_QK) { ka = nk; qa = nq; }
;         }
;         __builtin_amdgcn_sched_barrier(0);
;     }
;     l += sa + sb;
;     return sa + sb;
; }
.Ldma_ns2_p0:
	ds_read_b64_tr_b16 v[8:9], v213 offset:34816
	ds_read_b64_tr_b16 v[6:7], v207 offset:32768
	ds_read_b64_tr_b16 v[146:147], v207 offset:33280
	ds_read_b64_tr_b16 v[174:175], v207 offset:33792
	ds_read_b64_tr_b16 v[182:183], v207 offset:34304
	ds_read_b64_tr_b16 v[148:149], v213 offset:35328
	ds_read_b64_tr_b16 v[176:177], v213 offset:35840
	ds_read_b64_tr_b16 v[184:185], v213 offset:36352
	s_waitcnt lgkmcnt(1)
	v_mfma_f32_32x32x16_bf16 v[34:49], v[2:5], v[6:9], v[34:49]
	ds_read_b128 v[6:9], v203 offset:8192
	ds_read_b128 v[150:153], v217
	ds_read_b128 v[186:189], v204 offset:8192
	ds_read_b128 v[226:229], v219
	v_exp_f32_e32 v15, v158
	v_exp_f32_e32 v239, v160
	v_mfma_f32_32x32x16_bf16 v[50:65], v[2:5], v[146:149], v[50:65]
	v_exp_f32_e32 v14, v159
	v_exp_f32_e32 v238, v161
	s_waitcnt lgkmcnt(2)
	v_mfma_f32_32x32x16_bf16 v[146:161], v[6:9], v[150:153], 0
	v_mfma_f32_32x32x16_bf16 v[66:81], v[2:5], v[174:177], v[66:81]
	ds_read_b64_tr_b16 v[6:7], v207 offset:36864
	ds_read_b64_tr_b16 v[8:9], v213 offset:38912
	ds_read_b64_tr_b16 v[176:177], v213 offset:39424
	ds_read_b64_tr_b16 v[174:175], v207 offset:37376
	ds_read_b128 v[230:233], v205 offset:8192
	ds_read_b128 v[234:237], v221
	v_exp_f32_e32 v241, v162
	v_exp_f32_e32 v240, v163
	v_mfma_f32_32x32x16_bf16 v[82:97], v[2:5], v[182:185], v[82:97]
	v_exp_f32_e32 v243, v164
	v_exp_f32_e32 v242, v165
	v_cvt_pk_bf16_f32 v2, v15, v14
	v_cvt_pk_bf16_f32 v3, v239, v238
	v_cvt_pk_bf16_f32 v4, v241, v240
	s_waitcnt lgkmcnt(2)
	v_mfma_f32_32x32x16_bf16 v[146:161], v[186:189], v[226:229], v[146:161]
	v_cvt_pk_bf16_f32 v5, v243, v242
	v_mfma_f32_32x32x16_bf16 v[34:49], v[10:13], v[6:9], v[34:49]
	ds_read_b64_tr_b16 v[6:7], v207 offset:37888
	ds_read_b64_tr_b16 v[8:9], v213 offset:39936
	ds_read_b64_tr_b16 v[164:165], v213 offset:40448
	ds_read_b64_tr_b16 v[162:163], v207 offset:38400
	ds_read_b128 v[182:185], v206 offset:8192
	ds_read_b128 v[186:189], v223
	v_mfma_f32_32x32x16_bf16 v[50:65], v[10:13], v[174:177], v[50:65]
	v_exp_f32_e32 v175, v166
	v_exp_f32_e32 v174, v167
	v_exp_f32_e32 v167, v168
	v_exp_f32_e32 v166, v169
	s_waitcnt lgkmcnt(2)
	v_mfma_f32_32x32x16_bf16 v[146:161], v[230:233], v[234:237], v[146:161]
	v_mfma_f32_32x32x16_bf16 v[66:81], v[10:13], v[6:9], v[66:81]
	v_exp_f32_e32 v169, v170
	v_exp_f32_e32 v168, v171
	v_exp_f32_e32 v171, v172
	v_exp_f32_e32 v170, v173
	v_mfma_f32_32x32x16_bf16 v[82:97], v[10:13], v[162:165], v[82:97]
	v_cvt_pk_bf16_f32 v6, v175, v174
	v_cvt_pk_bf16_f32 v7, v167, v166
	v_cvt_pk_bf16_f32 v8, v169, v168
	v_cvt_pk_bf16_f32 v9, v171, v170
	v_add_f32_e64 v10, v238, v14
	v_add_f32_e64 v11, v239, v15
	s_waitcnt lgkmcnt(0)
	v_mfma_f32_32x32x16_bf16 v[146:161], v[182:185], v[186:189], v[146:161]
	v_add_f32_e64 v10, v240, v10
	v_add_f32_e64 v11, v241, v11
	v_add_f32_e64 v10, v242, v10
	v_add_f32_e64 v11, v243, v11
	v_add_f32_e64 v10, v174, v10
	v_add_f32_e64 v11, v175, v11
	v_add_f32_e32 v10, v166, v10
	v_add_f32_e32 v11, v167, v11
	v_add_f32_e32 v10, v168, v10
	v_add_f32_e32 v11, v169, v11
	v_add_f32_e32 v10, v170, v10
	v_add_f32_e32 v11, v171, v11
	v_add_f32_e32 v10, v10, v11
	v_cmp_nge_f32_e32 vcc, s58, v10
	s_cbranch_vccnz .Lfix_slow_2

; template <bool HAS_PV, bool HAS_QK, bool C1> ...
;     s16x4 vlo[2], vhi[2]; bf16x8 ka, qa;
;     if (HAS_PV) {
; #pragma unroll
;         for (int u = 0; u < 2; ++u) { vlo[u] = vtr(vb + vaddr[0] + u * 512); vhi[u] = vtr(vb + vaddr[1] + u * 512); } }
;     if (HAS_QK) { const int ad = C1 ? sub1(kaddr[0]) : kaddr[0]; ka = *(const ATT_LAS bf16x8*)(kb + ad); qa = *(const ATT_LAS bf16x8*)(qb_ + ad);
; #pragma unroll
;         for (int i = 0; i < 16; ++i) Snext[i] = 0.f; }
;     float sa = 0.f, sb = 0.f;
; #pragma unroll
;     for (int g = 0; g < 4; ++g) {
;         s16x4 nlo[2], nhi[2]; bf16x8 nk, nq;
;         if (g < 3) {
;             if (HAS_PV) {
; #pragma unroll
;                 for (int u = 0; u < 2; ++u) { const int off = (2 * ((g + 1) & 1) + u) * 512 + ((g + 1) >> 1) * 4096; nlo[u] = vtr(vb + vaddr[0] + off); nhi[u] = vtr(vb + vaddr[1] + off); } }
;             if (HAS_QK) { const int ad = C1 ? sub1(kaddr[g + 1]) : kaddr[g + 1]; nk = *(const ATT_LAS bf16x8*)(kb + ad); nq = *(const ATT_LAS bf16x8*)(qb_ + ad); }
;         }
;         if (HAS_PV) { const bf16x8 pa = __builtin_bit_cast(bf16x8, pkin[g >> 1]);
; #pragma unroll
;             for (int u = 0; u < 2; ++u) { const bf16x8 vf = __builtin_shufflevector(vlo[u], vhi[u], 0, 1, 2, 3, 4, 5, 6, 7); Opv[2 * (g & 1) + u] = ATT_MFMA(pa, vf, Opv[2 * (g & 1) + u]); } }
;         if (HAS_QK) Snext = ATT_MFMA(ka, qa, Snext);
; #pragma unroll
;         for (int e = 4 * g; e < 4 * g + 4; e += 2) { Scur[e] = __builtin_amdgcn_exp2f(Scur[e] - m); Scur[e + 1] = __builtin_amdgcn_exp2f(Scur[e + 1] - m); sa += Scur[e]; sb += Scur[e + 1]; }
;         if (g & 1) pkout[g >> 1] = (u32x4){cvtpk(Scur[4 * g - 4], Scur[4 * g - 3]), cvtpk(Scur[4 * g - 2], Scur[4 * g - 1]), cvtpk(Scur[4 * g], Scur[4 * g + 1]), cvtpk(Scur[4 * g + 2], Scur[4 * g + 3])};
;         if (g < 3) {
;             if (HAS_PV) {
; #pragma unroll
;                 for (int u = 0; u < 2; ++u) { vlo[u] = nlo[u]; vhi[u] = nhi[u]; } }
;             if (HAS_QK) { ka = nk; qa = nq; }
;         }
;         __builtin_amdgcn_sched_barrier(0);
;     }
;     l += sa + sb;
;     return sa + sb;
; }
; __device__ __forceinline__ void tile_body(bool MASK, const ATT_LAS unsigned char* kb, const ATT_LAS unsigned char* vb, const ATT_LAS unsigned char* qbase, const int (&kaddr)[4], const int (&vaddr)[2], ...
;     ...
;     apply_mask(MASK, Sa, kvrel + 32, r, h); ls = l1;
.Ldma_ns3_p0:
	ds_read_b64_tr_b16 v[10:11], v207 offset:32768
	ds_read_b64_tr_b16 v[12:13], v213 offset:34816
	ds_read_b64_tr_b16 v[164:165], v213 offset:35328
	ds_read_b64_tr_b16 v[162:163], v207 offset:33280
	s_waitcnt lgkmcnt(0)
	v_mfma_f32_32x32x16_bf16 v[130:145], v[2:5], v[10:13], v[130:145]
	ds_read_b128 v[166:169], v209 offset:8192
	ds_read_b128 v[170:173], v244
	ds_read_b64_tr_b16 v[10:11], v207 offset:33792
	ds_read_b64_tr_b16 v[12:13], v213 offset:35840
	ds_read_b64_tr_b16 v[184:185], v213 offset:36352
	ds_read_b64_tr_b16 v[182:183], v207 offset:34304
	v_mfma_f32_32x32x16_bf16 v[114:129], v[2:5], v[162:165], v[114:129]
	ds_read_b128 v[186:189], v210 offset:8192
	ds_read_b128 v[224:227], v245
	v_exp_f32_e32 v15, v146
	v_exp_f32_e32 v237, v148
	s_waitcnt lgkmcnt(2)
	v_mfma_f32_32x32x16_bf16 v[162:177], v[166:169], v[170:173], 0
	v_exp_f32_e32 v14, v147
	v_exp_f32_e32 v236, v149
	v_mfma_f32_32x32x16_bf16 v[98:113], v[2:5], v[10:13], v[98:113]
	ds_read_b64_tr_b16 v[146:147], v207 offset:36864
	ds_read_b64_tr_b16 v[148:149], v213 offset:38912
	ds_read_b64_tr_b16 v[230:231], v213 offset:39424
	ds_read_b64_tr_b16 v[228:229], v207 offset:37376
	ds_read_b128 v[10:13], v211 offset:8192
	ds_read_b128 v[232:235], v246
	v_mfma_f32_32x32x16_bf16 v[18:33], v[2:5], v[182:185], v[18:33]
	v_exp_f32_e32 v239, v150
	v_exp_f32_e32 v241, v152
	v_exp_f32_e32 v238, v151
	s_waitcnt lgkmcnt(4)
	v_mfma_f32_32x32x16_bf16 v[162:177], v[186:189], v[224:227], v[162:177]
	v_exp_f32_e32 v240, v153
	v_cvt_pk_bf16_f32 v2, v15, v14
	v_cvt_pk_bf16_f32 v3, v237, v236
	v_cvt_pk_bf16_f32 v4, v239, v238
	v_cvt_pk_bf16_f32 v5, v241, v240
	v_mfma_f32_32x32x16_bf16 v[130:145], v[6:9], v[146:149], v[130:145]
	ds_read_b64_tr_b16 v[146:147], v207 offset:37888
	ds_read_b64_tr_b16 v[148:149], v213 offset:39936
	ds_read_b64_tr_b16 v[152:153], v213 offset:40448
	ds_read_b64_tr_b16 v[150:151], v207 offset:38400
	ds_read_b128 v[182:185], v212 offset:8192
	ds_read_b128 v[186:189], v247
	s_waitcnt lgkmcnt(4)
	v_mfma_f32_32x32x16_bf16 v[114:129], v[6:9], v[228:231], v[114:129]
	v_exp_f32_e32 v225, v154
	v_exp_f32_e32 v224, v155
	v_exp_f32_e32 v155, v156
	v_mfma_f32_32x32x16_bf16 v[162:177], v[10:13], v[232:235], v[162:177]
	v_exp_f32_e32 v154, v157
	v_exp_f32_e32 v157, v158
	v_mfma_f32_32x32x16_bf16 v[98:113], v[6:9], v[146:149], v[98:113]
	v_exp_f32_e32 v156, v159
	v_exp_f32_e32 v147, v160
	v_exp_f32_e32 v146, v161
	v_cvt_pk_bf16_f32 v10, v225, v224
	v_cvt_pk_bf16_f32 v11, v155, v154
	s_waitcnt lgkmcnt(0)
	v_mfma_f32_32x32x16_bf16 v[18:33], v[6:9], v[150:153], v[18:33]
	v_cvt_pk_bf16_f32 v12, v157, v156
	v_cvt_pk_bf16_f32 v13, v147, v146
	v_add_f32_e64 v6, v236, v14
	v_add_f32_e64 v7, v237, v15
	v_add_f32_e64 v6, v238, v6
	v_add_f32_e64 v7, v239, v7
	v_mfma_f32_32x32x16_bf16 v[162:177], v[182:185], v[186:189], v[162:177]
	v_add_f32_e64 v6, v240, v6
	v_add_f32_e64 v7, v241, v7
	v_add_f32_e64 v6, v224, v6
	v_add_f32_e64 v7, v225, v7
	v_add_f32_e64 v6, v154, v6
	v_add_f32_e64 v7, v155, v7
	v_add_f32_e32 v6, v156, v6
	v_add_f32_e32 v7, v157, v7
	v_add_f32_e32 v6, v146, v6
	v_add_f32_e32 v7, v147, v7
	v_add_f32_e32 v6, v6, v7
	v_cmp_nge_f32_e32 vcc, s58, v6
	s_cbranch_vccnz .Lfix_slow_3

; template <bool HAS_PV, bool HAS_QK, bool C1> ...
;     s16x4 vlo[2], vhi[2]; bf16x8 ka, qa;
;     if (HAS_PV) {
; #pragma unroll
;         for (int u = 0; u < 2; ++u) { vlo[u] = vtr(vb + vaddr[0] + u * 512); vhi[u] = vtr(vb + vaddr[1] + u * 512); } }
;     if (HAS_QK) { const int ad = C1 ? sub1(kaddr[0]) : kaddr[0]; ka = *(const ATT_LAS bf16x8*)(kb + ad); qa = *(const ATT_LAS bf16x8*)(qb_ + ad);
; #pragma unroll
;         for (int i = 0; i < 16; ++i) Snext[i] = 0.f; }
;     float sa = 0.f, sb = 0.f;
; #pragma unroll
;     for (int g = 0; g < 4; ++g) {
;         s16x4 nlo[2], nhi[2]; bf16x8 nk, nq;
;         if (g < 3) {
;             if (HAS_PV) {
; #pragma unroll
;                 for (int u = 0; u < 2; ++u) { const int off = (2 * ((g + 1) & 1) + u) * 512 + ((g + 1) >> 1) * 4096; nlo[u] = vtr(vb + vaddr[0] + off); nhi[u] = vtr(vb + vaddr[1] + off); } }
;             if (HAS_QK) { const int ad = C1 ? sub1(kaddr[g + 1]) : kaddr[g + 1]; nk = *(const ATT_LAS bf16x8*)(kb + ad); nq = *(const ATT_LAS bf16x8*)(qb_ + ad); }
;         }
;         if (HAS_PV) { const bf16x8 pa = __builtin_bit_cast(bf16x8, pkin[g >> 1]);
; #pragma unroll
;             for (int u = 0; u < 2; ++u) { const bf16x8 vf = __builtin_shufflevector(vlo[u], vhi[u], 0, 1, 2, 3, 4, 5, 6, 7); Opv[2 * (g & 1) + u] = ATT_MFMA(pa, vf, Opv[2 * (g & 1) + u]); } }
;         if (HAS_QK) Snext = ATT_MFMA(ka, qa, Snext);
; #pragma unroll
;         for (int e = 4 * g; e < 4 * g + 4; e += 2) { Scur[e] = __builtin_amdgcn_exp2f(Scur[e] - m); Scur[e + 1] = __builtin_amdgcn_exp2f(Scur[e + 1] - m); sa += Scur[e]; sb += Scur[e + 1]; }
;         if (g & 1) pkout[g >> 1] = (u32x4){cvtpk(Scur[4 * g - 4], Scur[4 * g - 3]), cvtpk(Scur[4 * g - 2], Scur[4 * g - 1]), cvtpk(Scur[4 * g], Scur[4 * g + 1]), cvtpk(Scur[4 * g + 2], Scur[4 * g + 3])};
;         if (g < 3) {
;             if (HAS_PV) {
; #pragma unroll
;                 for (int u = 0; u < 2; ++u) { vlo[u] = nlo[u]; vhi[u] = nhi[u]; } }
;             if (HAS_QK) { ka = nk; qa = nq; }
;         }
;         __builtin_amdgcn_sched_barrier(0);
;     }
;     l += sa + sb;
;     return sa + sb;
; }
; __device__ __forceinline__ void pv_issue(f32x16 (&O)[4], const u32x4 (&pk)[2], const ATT_LAS unsigned char* vb, const int (&vaddr)[2]) {
; #pragma unroll
;     for (int s_ = 0; s_ < 2; ++s_) { const bf16x8 pa = __builtin_bit_cast(bf16x8, pk[s_]);
; #pragma unroll
.Lns_341_p0:
	ds_read_b64_tr_b16 v[8:9], v213 offset:43008
	ds_read_b64_tr_b16 v[6:7], v207 offset:40960
	ds_read_b64_tr_b16 v[146:147], v207 offset:41472
	ds_read_b64_tr_b16 v[150:151], v207 offset:41984
	ds_read_b64_tr_b16 v[154:155], v207 offset:42496
	ds_read_b64_tr_b16 v[148:149], v213 offset:43520
	ds_read_b64_tr_b16 v[152:153], v213 offset:44032
	ds_read_b64_tr_b16 v[156:157], v213 offset:44544
	s_waitcnt lgkmcnt(1)
	v_mfma_f32_32x32x16_bf16 v[34:49], v[2:5], v[6:9], v[34:49]
	v_exp_f32_e32 v15, v162
	v_exp_f32_e32 v14, v163
	v_exp_f32_e32 v163, v164
	v_mfma_f32_32x32x16_bf16 v[50:65], v[2:5], v[146:149], v[50:65]
	v_exp_f32_e32 v162, v165
	v_mfma_f32_32x32x16_bf16 v[66:81], v[2:5], v[150:153], v[66:81]
	ds_read_b64_tr_b16 v[146:147], v207 offset:45056
	ds_read_b64_tr_b16 v[148:149], v213 offset:47104
	ds_read_b64_tr_b16 v[160:161], v213 offset:47616
	ds_read_b64_tr_b16 v[158:159], v207 offset:45568
	v_exp_f32_e32 v165, v166
	v_exp_f32_e32 v164, v167
	v_exp_f32_e32 v167, v168
	s_waitcnt lgkmcnt(2)
	v_mfma_f32_32x32x16_bf16 v[82:97], v[2:5], v[154:157], v[82:97]
	v_exp_f32_e32 v166, v169
	v_cvt_pk_bf16_f32 v6, v15, v14
	v_cvt_pk_bf16_f32 v7, v163, v162
	v_cvt_pk_bf16_f32 v8, v165, v164
	v_cvt_pk_bf16_f32 v9, v167, v166
	v_mfma_f32_32x32x16_bf16 v[34:49], v[10:13], v[146:149], v[34:49]
	ds_read_b64_tr_b16 v[2:3], v207 offset:46080
	ds_read_b64_tr_b16 v[4:5], v213 offset:48128
	ds_read_b64_tr_b16 v[152:153], v213 offset:48640
	ds_read_b64_tr_b16 v[150:151], v207 offset:46592
	v_exp_f32_e32 v147, v170
	v_exp_f32_e32 v146, v171
	v_exp_f32_e32 v149, v172
	s_waitcnt lgkmcnt(0)
	v_mfma_f32_32x32x16_bf16 v[50:65], v[10:13], v[158:161], v[50:65]
	v_exp_f32_e32 v148, v173
	v_mfma_f32_32x32x16_bf16 v[66:81], v[10:13], v[2:5], v[66:81]
	v_exp_f32_e32 v155, v174
	v_exp_f32_e32 v154, v175
	v_exp_f32_e32 v157, v176
	v_mfma_f32_32x32x16_bf16 v[82:97], v[10:13], v[150:153], v[82:97]
	v_add_f32_e64 v10, v162, v14
	v_add_f32_e64 v11, v163, v15
	v_exp_f32_e32 v156, v177
	v_add_f32_e32 v10, v164, v10
	v_add_f32_e32 v11, v165, v11
	v_cvt_pk_bf16_f32 v2, v147, v146
	v_cvt_pk_bf16_f32 v3, v149, v148
	v_cvt_pk_bf16_f32 v4, v155, v154
	v_cvt_pk_bf16_f32 v5, v157, v156
	v_add_f32_e32 v10, v166, v10
	v_add_f32_e32 v11, v167, v11
	v_add_f32_e32 v10, v146, v10
	v_add_f32_e32 v11, v147, v11
	v_add_f32_e32 v10, v148, v10
	v_add_f32_e32 v11, v149, v11
	v_add_f32_e32 v10, v154, v10
	v_add_f32_e32 v11, v155, v11
	v_add_f32_e32 v10, v156, v10
	v_add_f32_e32 v11, v157, v11
	v_add_f32_e32 v10, v10, v11
	v_cmp_nge_f32_e32 vcc, s58, v10
	s_cbranch_vccnz .Lfix_slow_4
	v_add_f32_e32 v224, v181, v10
	ds_read_b64_tr_b16 v[12:13], v213 offset:43008
	ds_read_b64_tr_b16 v[10:11], v207 offset:40960
	ds_read_b64_tr_b16 v[146:147], v207 offset:41472
	ds_read_b64_tr_b16 v[150:151], v207 offset:41984
	ds_read_b64_tr_b16 v[154:155], v207 offset:42496
	ds_read_b64_tr_b16 v[148:149], v213 offset:43520
	ds_read_b64_tr_b16 v[152:153], v213 offset:44032
	ds_read_b64_tr_b16 v[156:157], v213 offset:44544
	ds_read_b64_tr_b16 v[160:161], v213 offset:47104
	ds_read_b64_tr_b16 v[158:159], v207 offset:45056
	ds_read_b64_tr_b16 v[162:163], v207 offset:45568
	ds_read_b64_tr_b16 v[166:167], v207 offset:46080
	ds_read_b64_tr_b16 v[170:171], v207 offset:46592
	ds_read_b64_tr_b16 v[164:165], v213 offset:47616
	ds_read_b64_tr_b16 v[168:169], v213 offset:48128
	s_waitcnt lgkmcnt(7)
	v_mfma_f32_32x32x16_bf16 v[130:145], v[6:9], v[10:13], v[130:145]
	v_mfma_f32_32x32x16_bf16 v[114:129], v[6:9], v[146:149], v[114:129]
	v_mfma_f32_32x32x16_bf16 v[98:113], v[6:9], v[150:153], v[98:113]
	v_mfma_f32_32x32x16_bf16 v[18:33], v[6:9], v[154:157], v[18:33]
	ds_read_b64_tr_b16 v[172:173], v213 offset:48640
	s_waitcnt lgkmcnt(0)
	v_mfma_f32_32x32x16_bf16 v[130:145], v[2:5], v[158:161], v[130:145]
	v_mfma_f32_32x32x16_bf16 v[114:129], v[2:5], v[162:165], v[114:129]
	v_mfma_f32_32x32x16_bf16 v[98:113], v[2:5], v[166:169], v[98:113]
	v_mfma_f32_32x32x16_bf16 v[18:33], v[2:5], v[170:173], v[18:33]
	s_add_i32 s80, s80, 64
	s_add_u32 s94, s94, 0x20000
	s_addc_u32 s95, s95, 0
	s_waitcnt vmcnt(0)
	s_add_u32 s92, s92, 0x20000
	s_addc_u32 s93, s93, 0
	s_cmp_eq_u32 s76, s79
	v_subrev_u32_e32 v214, 64, v214
	s_barrier
	s_cbranch_scc0 .LBB0_289
	s_branch .LBB0_352

; #define ATT_LAS __attribute__((address_space(3)))
; __device__ __forceinline__ int sub1(int a) { int v = a ^ 128; asm volatile("" : "+v"(v)); return v; }
; #define ATT_MFMA(a, b, c) __builtin_amdgcn_mfma_f32_32x32x16_bf16((a), (b), (c), 0, 0, 0)
; template <bool C1> __device__ __forceinline__ void qk_issue(f32x16& s0, const ATT_LAS unsigned char* kb, const ATT_LAS unsigned char* qb_, const int (&kaddr)[4]) {
; #pragma unroll
;     for (int i = 0; i < 16; ++i) s0[i] = 0.f;
; #pragma unroll
;     for (int ds = 0; ds < 4; ++ds) {
;         const int ad = C1 ? sub1(kaddr[ds]) : kaddr[ds];
;         const bf16x8 a0 = *(const ATT_LAS bf16x8*)(kb + ad);
;         const bf16x8 qv = *(const ATT_LAS bf16x8*)(qb_ + ad);
;         s0 = ATT_MFMA(a0, qv, s0);
;     }
; }
; __device__ __forceinline__ void tile_body(bool MASK, const ATT_LAS unsigned char* kb, const ATT_LAS unsigned char* vb, const ATT_LAS unsigned char* qbase, const int (&kaddr)[4], const int (&vaddr)[2], ...
;     ...
;     qk_issue<false>(Sa, kb, qbase, kaddr);
;     apply_mask(MASK, Sa, kvrel, r, h); ls = l1;
.Lpar1:
	ds_read_b128 v[2:5], v203 offset:16384
	ds_read_b128 v[6:9], v217
	ds_read_b128 v[10:13], v204 offset:16384
	ds_read_b128 v[146:149], v219
	ds_read_b128 v[150:153], v205 offset:16384
	ds_read_b128 v[154:157], v221
	ds_read_b128 v[158:161], v206 offset:16384
	ds_read_b128 v[162:165], v223
	s_cmpk_gt_i32 s80, 0xffc1
	s_cselect_b64 s[36:37], -1, 0
	s_cmpk_lt_i32 s80, 0xffc2
	s_waitcnt lgkmcnt(4)
	v_mfma_f32_32x32x16_bf16 v[170:185], v[2:5], v[6:9], 0
	v_mfma_f32_32x32x16_bf16 v[170:185], v[10:13], v[146:149], v[170:185]
	s_waitcnt lgkmcnt(0)
	v_mfma_f32_32x32x16_bf16 v[170:185], v[150:153], v[154:157], v[170:185]
	v_mfma_f32_32x32x16_bf16 v[170:185], v[158:161], v[162:165], v[170:185]
	s_cbranch_scc0 .Lhead_mask_p1

; #define ATT_LAS __attribute__((address_space(3)))
; __device__ __forceinline__ unsigned cvtpk(float lo, float hi) { unsigned r; asm volatile("v_cvt_pk_bf16_f32 %0, %1, %2" : "=v"(r) : "v"(lo), "v"(hi)); return r; }
; template <bool HAS_PV, bool HAS_QK, bool C1> ...
;     s16x4 vlo[2], vhi[2]; bf16x8 ka, qa;
;     if (HAS_PV) {
; #pragma unroll
;         for (int u = 0; u < 2; ++u) { vlo[u] = vtr(vb + vaddr[0] + u * 512); vhi[u] = vtr(vb + vaddr[1] + u * 512); } }
;     if (HAS_QK) { const int ad = C1 ? sub1(kaddr[0]) : kaddr[0]; ka = *(const ATT_LAS bf16x8*)(kb + ad); qa = *(const ATT_LAS bf16x8*)(qb_ + ad);
; #pragma unroll
;         for (int i = 0; i < 16; ++i) Snext[i] = 0.f; }
;     float sa = 0.f, sb = 0.f;
; #pragma unroll
;     for (int g = 0; g < 4; ++g) {
;         s16x4 nlo[2], nhi[2]; bf16x8 nk, nq;
;         if (g < 3) {
;             if (HAS_PV) {
; #pragma unroll
;                 for (int u = 0; u < 2; ++u) { const int off = (2 * ((g + 1) & 1) + u) * 512 + ((g + 1) >> 1) * 4096; nlo[u] = vtr(vb + vaddr[0] + off); nhi[u] = vtr(vb + vaddr[1] + off); } }
;             if (HAS_QK) { const int ad = C1 ? sub1(kaddr[g + 1]) : kaddr[g + 1]; nk = *(const ATT_LAS bf16x8*)(kb + ad); nq = *(const ATT_LAS bf16x8*)(qb_ + ad); }
;         }
;         if (HAS_PV) { const bf16x8 pa = __builtin_bit_cast(bf16x8, pkin[g >> 1]);
; #pragma unroll
;             for (int u = 0; u < 2; ++u) { const bf16x8 vf = __builtin_shufflevector(vlo[u], vhi[u], 0, 1, 2, 3, 4, 5, 6, 7); Opv[2 * (g & 1) + u] = ATT_MFMA(pa, vf, Opv[2 * (g & 1) + u]); } }
;         if (HAS_QK) Snext = ATT_MFMA(ka, qa, Snext);
; #pragma unroll
;         for (int e = 4 * g; e < 4 * g + 4; e += 2) { Scur[e] = __builtin_amdgcn_exp2f(Scur[e] - m); Scur[e + 1] = __builtin_amdgcn_exp2f(Scur[e + 1] - m); sa += Scur[e]; sb += Scur[e + 1]; }
;         if (g & 1) pkout[g >> 1] = (u32x4){cvtpk(Scur[4 * g - 4], Scur[4 * g - 3]), cvtpk(Scur[4 * g - 2], Scur[4 * g - 1]), cvtpk(Scur[4 * g], Scur[4 * g + 1]), cvtpk(Scur[4 * g + 2], Scur[4 * g + 3])};
;         if (g < 3) {
;             if (HAS_PV) {
; #pragma unroll
;                 for (int u = 0; u < 2; ++u) { vlo[u] = nlo[u]; vhi[u] = nhi[u]; } }
;             if (HAS_QK) { ka = nk; qa = nq; }
;         }
;         __builtin_amdgcn_sched_barrier(0);
;     }
;     l += sa + sb;
;     return sa + sb;
; }
.Lns_296_p1:
	ds_read_b128 v[2:5], v209 offset:16384
	ds_read_b128 v[6:9], v244
	s_nop 1
	ds_read_b128 v[10:13], v210 offset:16384
	ds_read_b128 v[146:149], v245
	v_exp_f32_e32 v15, v170
	v_exp_f32_e32 v14, v171
	v_exp_f32_e32 v155, v172
	v_exp_f32_e32 v154, v173
	s_waitcnt lgkmcnt(2)
	v_mfma_f32_32x32x16_bf16 v[158:173], v[2:5], v[6:9], 0
	s_waitcnt lgkmcnt(0)
	v_mfma_f32_32x32x16_bf16 v[158:173], v[10:13], v[146:149], v[158:173]
	ds_read_b128 v[6:9], v211 offset:16384
	ds_read_b128 v[150:153], v246
	v_exp_f32_e32 v157, v174
	v_exp_f32_e32 v156, v175
	v_exp_f32_e32 v175, v176
	v_exp_f32_e32 v174, v177
	v_cvt_pk_bf16_f32 v2, v15, v14
	v_cvt_pk_bf16_f32 v3, v155, v154
	v_cvt_pk_bf16_f32 v4, v157, v156
	v_cvt_pk_bf16_f32 v5, v175, v174
	s_waitcnt lgkmcnt(0)
	v_mfma_f32_32x32x16_bf16 v[158:173], v[6:9], v[150:153], v[158:173]
	ds_read_b128 v[10:13], v212 offset:16384
	ds_read_b128 v[146:149], v247
	v_exp_f32_e32 v177, v178
	v_exp_f32_e32 v176, v179
	v_exp_f32_e32 v179, v180
	v_exp_f32_e32 v178, v181
	s_waitcnt lgkmcnt(0)
	v_mfma_f32_32x32x16_bf16 v[158:173], v[10:13], v[146:149], v[158:173]
	v_exp_f32_e32 v7, v182
	v_add_f32_e32 v14, v154, v14
	v_add_f32_e32 v15, v155, v15
	v_exp_f32_e32 v6, v183
	v_exp_f32_e32 v9, v184
	v_add_f32_e32 v14, v156, v14
	v_add_f32_e32 v15, v157, v15
	v_exp_f32_e32 v8, v185
	v_add_f32_e32 v14, v174, v14
	v_add_f32_e32 v15, v175, v15
	v_cvt_pk_bf16_f32 v10, v177, v176
	v_cvt_pk_bf16_f32 v11, v179, v178
	v_cvt_pk_bf16_f32 v12, v7, v6
	v_cvt_pk_bf16_f32 v13, v9, v8
	v_add_f32_e32 v14, v176, v14
	v_add_f32_e32 v15, v177, v15
	v_add_f32_e32 v14, v178, v14
	v_add_f32_e32 v15, v179, v15
	v_add_f32_e32 v6, v6, v14
	v_add_f32_e32 v7, v7, v15
	v_add_f32_e32 v6, v8, v6
	v_add_f32_e32 v7, v9, v7
	v_add_f32_e32 v6, v6, v7
	v_cmp_nge_f32_e32 vcc, s58, v6
	s_andn2_b64 s[4:5], exec, s[36:37]
	s_cbranch_vccnz .Lfix_slow_1

; #define ATT_LAS __attribute__((address_space(3)))
; __device__ __forceinline__ unsigned cvtpk(float lo, float hi) { unsigned r; asm volatile("v_cvt_pk_bf16_f32 %0, %1, %2" : "=v"(r) : "v"(lo), "v"(hi)); return r; }
; template <bool HAS_PV, bool HAS_QK, bool C1> ...
;     s16x4 vlo[2], vhi[2]; bf16x8 ka, qa;
;     if (HAS_PV) {
; #pragma unroll
;         for (int u = 0; u < 2; ++u) { vlo[u] = vtr(vb + vaddr[0] + u * 512); vhi[u] = vtr(vb + vaddr[1] + u * 512); } }
;     if (HAS_QK) { const int ad = C1 ? sub1(kaddr[0]) : kaddr[0]; ka = *(const ATT_LAS bf16x8*)(kb + ad); qa = *(const ATT_LAS bf16x8*)(qb_ + ad);
; #pragma unroll
;         for (int i = 0; i < 16; ++i) Snext[i] = 0.f; }
;     float sa = 0.f, sb = 0.f;
; #pragma unroll
;     for (int g = 0; g < 4; ++g) {
;         s16x4 nlo[2], nhi[2]; bf16x8 nk, nq;
;         if (g < 3) {
;             if (HAS_PV) {
; #pragma unroll
;                 for (int u = 0; u < 2; ++u) { const int off = (2 * ((g + 1) & 1) + u) * 512 + ((g + 1) >> 1) * 4096; nlo[u] = vtr(vb + vaddr[0] + off); nhi[u] = vtr(vb + vaddr[1] + off); } }
;             if (HAS_QK) { const int ad = C1 ? sub1(kaddr[g + 1]) : kaddr[g + 1]; nk = *(const ATT_LAS bf16x8*)(kb + ad); nq = *(const ATT_LAS bf16x8*)(qb_ + ad); }
;         }
;         if (HAS_PV) { const bf16x8 pa = __builtin_bit_cast(bf16x8, pkin[g >> 1]);
; #pragma unroll
;             for (int u = 0; u < 2; ++u) { const bf16x8 vf = __builtin_shufflevector(vlo[u], vhi[u], 0, 1, 2, 3, 4, 5, 6, 7); Opv[2 * (g & 1) + u] = ATT_MFMA(pa, vf, Opv[2 * (g & 1) + u]); } }
;         if (HAS_QK) Snext = ATT_MFMA(ka, qa, Snext);
; #pragma unroll
;         for (int e = 4 * g; e < 4 * g + 4; e += 2) { Scur[e] = __builtin_amdgcn_exp2f(Scur[e] - m); Scur[e + 1] = __builtin_amdgcn_exp2f(Scur[e + 1] - m); sa += Scur[e]; sb += Scur[e + 1]; }
;         if (g & 1) pkout[g >> 1] = (u32x4){cvtpk(Scur[4 * g - 4], Scur[4 * g - 3]), cvtpk(Scur[4 * g - 2], Scur[4 * g - 1]), cvtpk(Scur[4 * g], Scur[4 * g + 1]), cvtpk(Scur[4 * g + 2], Scur[4 * g + 3])};
;         if (g < 3) {
;             if (HAS_PV) {
; #pragma unroll
;                 for (int u = 0; u < 2; ++u) { vlo[u] = nlo[u]; vhi[u] = nhi[u]; } }
;             if (HAS_QK) { ka = nk; qa = nq; }
;         }
;         __builtin_amdgcn_sched_barrier(0);
;     }
;     l += sa + sb;
;     return sa + sb;
; }
.Ldma_ns2_p1:
	ds_read_b64_tr_b16 v[8:9], v213 offset:51200
	ds_read_b64_tr_b16 v[6:7], v207 offset:49152
	ds_read_b64_tr_b16 v[146:147], v207 offset:49664
	ds_read_b64_tr_b16 v[174:175], v207 offset:50176
	ds_read_b64_tr_b16 v[182:183], v207 offset:50688
	ds_read_b64_tr_b16 v[148:149], v213 offset:51712
	ds_read_b64_tr_b16 v[176:177], v213 offset:52224
	ds_read_b64_tr_b16 v[184:185], v213 offset:52736
	s_waitcnt lgkmcnt(1)
	v_mfma_f32_32x32x16_bf16 v[34:49], v[2:5], v[6:9], v[34:49]
	ds_read_b128 v[6:9], v203 offset:24576
	ds_read_b128 v[150:153], v217
	ds_read_b128 v[186:189], v204 offset:24576
	ds_read_b128 v[226:229], v219
	v_exp_f32_e32 v15, v158
	v_exp_f32_e32 v239, v160
	v_mfma_f32_32x32x16_bf16 v[50:65], v[2:5], v[146:149], v[50:65]
	v_exp_f32_e32 v14, v159
	v_exp_f32_e32 v238, v161
	s_waitcnt lgkmcnt(2)
	v_mfma_f32_32x32x16_bf16 v[146:161], v[6:9], v[150:153], 0
	v_mfma_f32_32x32x16_bf16 v[66:81], v[2:5], v[174:177], v[66:81]
	ds_read_b64_tr_b16 v[6:7], v207 offset:53248
	ds_read_b64_tr_b16 v[8:9], v213 offset:55296
	ds_read_b64_tr_b16 v[176:177], v213 offset:55808
	ds_read_b64_tr_b16 v[174:175], v207 offset:53760
	ds_read_b128 v[230:233], v205 offset:24576
	ds_read_b128 v[234:237], v221
	v_exp_f32_e32 v241, v162
	v_exp_f32_e32 v240, v163
	v_mfma_f32_32x32x16_bf16 v[82:97], v[2:5], v[182:185], v[82:97]
	v_exp_f32_e32 v243, v164
	v_exp_f32_e32 v242, v165
	v_cvt_pk_bf16_f32 v2, v15, v14
	v_cvt_pk_bf16_f32 v3, v239, v238
	v_cvt_pk_bf16_f32 v4, v241, v240
	s_waitcnt lgkmcnt(2)
	v_mfma_f32_32x32x16_bf16 v[146:161], v[186:189], v[226:229], v[146:161]
	v_cvt_pk_bf16_f32 v5, v243, v242
	v_mfma_f32_32x32x16_bf16 v[34:49], v[10:13], v[6:9], v[34:49]
	ds_read_b64_tr_b16 v[6:7], v207 offset:54272
	ds_read_b64_tr_b16 v[8:9], v213 offset:56320
	ds_read_b64_tr_b16 v[164:165], v213 offset:56832
	ds_read_b64_tr_b16 v[162:163], v207 offset:54784
	ds_read_b128 v[182:185], v206 offset:24576
	ds_read_b128 v[186:189], v223
	v_mfma_f32_32x32x16_bf16 v[50:65], v[10:13], v[174:177], v[50:65]
	v_exp_f32_e32 v175, v166
	v_exp_f32_e32 v174, v167
	v_exp_f32_e32 v167, v168
	v_exp_f32_e32 v166, v169
	s_waitcnt lgkmcnt(2)
	v_mfma_f32_32x32x16_bf16 v[146:161], v[230:233], v[234:237], v[146:161]
	v_mfma_f32_32x32x16_bf16 v[66:81], v[10:13], v[6:9], v[66:81]
	v_exp_f32_e32 v169, v170
	v_exp_f32_e32 v168, v171
	v_exp_f32_e32 v171, v172
	v_exp_f32_e32 v170, v173
	v_mfma_f32_32x32x16_bf16 v[82:97], v[10:13], v[162:165], v[82:97]
	v_cvt_pk_bf16_f32 v6, v175, v174
	v_cvt_pk_bf16_f32 v7, v167, v166
	v_cvt_pk_bf16_f32 v8, v169, v168
	v_cvt_pk_bf16_f32 v9, v171, v170
	v_add_f32_e64 v10, v238, v14
	v_add_f32_e64 v11, v239, v15
	s_waitcnt lgkmcnt(0)
	v_mfma_f32_32x32x16_bf16 v[146:161], v[182:185], v[186:189], v[146:161]
	v_add_f32_e64 v10, v240, v10
	v_add_f32_e64 v11, v241, v11
	v_add_f32_e64 v10, v242, v10
	v_add_f32_e64 v11, v243, v11
	v_add_f32_e64 v10, v174, v10
	v_add_f32_e64 v11, v175, v11
	v_add_f32_e32 v10, v166, v10
	v_add_f32_e32 v11, v167, v11
	v_add_f32_e32 v10, v168, v10
	v_add_f32_e32 v11, v169, v11
	v_add_f32_e32 v10, v170, v10
	v_add_f32_e32 v11, v171, v11
	v_add_f32_e32 v10, v10, v11
	v_cmp_nge_f32_e32 vcc, s58, v10
	s_cbranch_vccnz .Lfix_slow_2

; template <bool HAS_PV, bool HAS_QK, bool C1> ...
;     s16x4 vlo[2], vhi[2]; bf16x8 ka, qa;
;     if (HAS_PV) {
; #pragma unroll
;         for (int u = 0; u < 2; ++u) { vlo[u] = vtr(vb + vaddr[0] + u * 512); vhi[u] = vtr(vb + vaddr[1] + u * 512); } }
;     if (HAS_QK) { const int ad = C1 ? sub1(kaddr[0]) : kaddr[0]; ka = *(const ATT_LAS bf16x8*)(kb + ad); qa = *(const ATT_LAS bf16x8*)(qb_ + ad);
; #pragma unroll
;         for (int i = 0; i < 16; ++i) Snext[i] = 0.f; }
;     float sa = 0.f, sb = 0.f;
; #pragma unroll
;     for (int g = 0; g < 4; ++g) {
;         s16x4 nlo[2], nhi[2]; bf16x8 nk, nq;
;         if (g < 3) {
;             if (HAS_PV) {
; #pragma unroll
;                 for (int u = 0; u < 2; ++u) { const int off = (2 * ((g + 1) & 1) + u) * 512 + ((g + 1) >> 1) * 4096; nlo[u] = vtr(vb + vaddr[0] + off); nhi[u] = vtr(vb + vaddr[1] + off); } }
;             if (HAS_QK) { const int ad = C1 ? sub1(kaddr[g + 1]) : kaddr[g + 1]; nk = *(const ATT_LAS bf16x8*)(kb + ad); nq = *(const ATT_LAS bf16x8*)(qb_ + ad); }
;         }
;         if (HAS_PV) { const bf16x8 pa = __builtin_bit_cast(bf16x8, pkin[g >> 1]);
; #pragma unroll
;             for (int u = 0; u < 2; ++u) { const bf16x8 vf = __builtin_shufflevector(vlo[u], vhi[u], 0, 1, 2, 3, 4, 5, 6, 7); Opv[2 * (g & 1) + u] = ATT_MFMA(pa, vf, Opv[2 * (g & 1) + u]); } }
;         if (HAS_QK) Snext = ATT_MFMA(ka, qa, Snext);
; #pragma unroll
;         for (int e = 4 * g; e < 4 * g + 4; e += 2) { Scur[e] = __builtin_amdgcn_exp2f(Scur[e] - m); Scur[e + 1] = __builtin_amdgcn_exp2f(Scur[e + 1] - m); sa += Scur[e]; sb += Scur[e + 1]; }
;         if (g & 1) pkout[g >> 1] = (u32x4){cvtpk(Scur[4 * g - 4], Scur[4 * g - 3]), cvtpk(Scur[4 * g - 2], Scur[4 * g - 1]), cvtpk(Scur[4 * g], Scur[4 * g + 1]), cvtpk(Scur[4 * g + 2], Scur[4 * g + 3])};
;         if (g < 3) {
;             if (HAS_PV) {
; #pragma unroll
;                 for (int u = 0; u < 2; ++u) { vlo[u] = nlo[u]; vhi[u] = nhi[u]; } }
;             if (HAS_QK) { ka = nk; qa = nq; }
;         }
;         __builtin_amdgcn_sched_barrier(0);
;     }
;     l += sa + sb;
;     return sa + sb;
; }
; __device__ __forceinline__ void tile_body(bool MASK, const ATT_LAS unsigned char* kb, const ATT_LAS unsigned char* vb, const ATT_LAS unsigned char* qbase, const int (&kaddr)[4], const int (&vaddr)[2], ...
;     ...
;     apply_mask(MASK, Sa, kvrel + 32, r, h); ls = l1;
.Ldma_ns3_p1:
	ds_read_b64_tr_b16 v[10:11], v207 offset:49152
	ds_read_b64_tr_b16 v[12:13], v213 offset:51200
	ds_read_b64_tr_b16 v[164:165], v213 offset:51712
	ds_read_b64_tr_b16 v[162:163], v207 offset:49664
	s_waitcnt lgkmcnt(0)
	v_mfma_f32_32x32x16_bf16 v[130:145], v[2:5], v[10:13], v[130:145]
	ds_read_b128 v[166:169], v209 offset:24576
	ds_read_b128 v[170:173], v244
	ds_read_b64_tr_b16 v[10:11], v207 offset:50176
	ds_read_b64_tr_b16 v[12:13], v213 offset:52224
	ds_read_b64_tr_b16 v[184:185], v213 offset:52736
	ds_read_b64_tr_b16 v[182:183], v207 offset:50688
	v_mfma_f32_32x32x16_bf16 v[114:129], v[2:5], v[162:165], v[114:129]
	ds_read_b128 v[186:189], v210 offset:24576
	ds_read_b128 v[224:227], v245
	v_exp_f32_e32 v15, v146
	v_exp_f32_e32 v237, v148
	s_waitcnt lgkmcnt(2)
	v_mfma_f32_32x32x16_bf16 v[162:177], v[166:169], v[170:173], 0
	v_exp_f32_e32 v14, v147
	v_exp_f32_e32 v236, v149
	v_mfma_f32_32x32x16_bf16 v[98:113], v[2:5], v[10:13], v[98:113]
	ds_read_b64_tr_b16 v[146:147], v207 offset:53248
	ds_read_b64_tr_b16 v[148:149], v213 offset:55296
	ds_read_b64_tr_b16 v[230:231], v213 offset:55808
	ds_read_b64_tr_b16 v[228:229], v207 offset:53760
	ds_read_b128 v[10:13], v211 offset:24576
	ds_read_b128 v[232:235], v246
	v_mfma_f32_32x32x16_bf16 v[18:33], v[2:5], v[182:185], v[18:33]
	v_exp_f32_e32 v239, v150
	v_exp_f32_e32 v241, v152
	v_exp_f32_e32 v238, v151
	s_waitcnt lgkmcnt(4)
	v_mfma_f32_32x32x16_bf16 v[162:177], v[186:189], v[224:227], v[162:177]
	v_exp_f32_e32 v240, v153
	v_cvt_pk_bf16_f32 v2, v15, v14
	v_cvt_pk_bf16_f32 v3, v237, v236
	v_cvt_pk_bf16_f32 v4, v239, v238
	v_cvt_pk_bf16_f32 v5, v241, v240
	v_mfma_f32_32x32x16_bf16 v[130:145], v[6:9], v[146:149], v[130:145]
	ds_read_b64_tr_b16 v[146:147], v207 offset:54272
	ds_read_b64_tr_b16 v[148:149], v213 offset:56320
	ds_read_b64_tr_b16 v[152:153], v213 offset:56832
	ds_read_b64_tr_b16 v[150:151], v207 offset:54784
	ds_read_b128 v[182:185], v212 offset:24576
	ds_read_b128 v[186:189], v247
	s_waitcnt lgkmcnt(4)
	v_mfma_f32_32x32x16_bf16 v[114:129], v[6:9], v[228:231], v[114:129]
	v_exp_f32_e32 v225, v154
	v_exp_f32_e32 v224, v155
	v_exp_f32_e32 v155, v156
	v_mfma_f32_32x32x16_bf16 v[162:177], v[10:13], v[232:235], v[162:177]
	v_exp_f32_e32 v154, v157
	v_exp_f32_e32 v157, v158
	v_mfma_f32_32x32x16_bf16 v[98:113], v[6:9], v[146:149], v[98:113]
	v_exp_f32_e32 v156, v159
	v_exp_f32_e32 v147, v160
	v_exp_f32_e32 v146, v161
	v_cvt_pk_bf16_f32 v10, v225, v224
	v_cvt_pk_bf16_f32 v11, v155, v154
	s_waitcnt lgkmcnt(0)
	v_mfma_f32_32x32x16_bf16 v[18:33], v[6:9], v[150:153], v[18:33]
	v_cvt_pk_bf16_f32 v12, v157, v156
	v_cvt_pk_bf16_f32 v13, v147, v146
	v_add_f32_e64 v6, v236, v14
	v_add_f32_e64 v7, v237, v15
	v_add_f32_e64 v6, v238, v6
	v_add_f32_e64 v7, v239, v7
	v_mfma_f32_32x32x16_bf16 v[162:177], v[182:185], v[186:189], v[162:177]
	v_add_f32_e64 v6, v240, v6
	v_add_f32_e64 v7, v241, v7
	v_add_f32_e64 v6, v224, v6
	v_add_f32_e64 v7, v225, v7
	v_add_f32_e64 v6, v154, v6
	v_add_f32_e64 v7, v155, v7
	v_add_f32_e32 v6, v156, v6
	v_add_f32_e32 v7, v157, v7
	v_add_f32_e32 v6, v146, v6
	v_add_f32_e32 v7, v147, v7
	v_add_f32_e32 v6, v6, v7
	v_cmp_nge_f32_e32 vcc, s58, v6
	s_cbranch_vccnz .Lfix_slow_3

; template <bool HAS_PV, bool HAS_QK, bool C1> ...
;     s16x4 vlo[2], vhi[2]; bf16x8 ka, qa;
;     if (HAS_PV) {
; #pragma unroll
;         for (int u = 0; u < 2; ++u) { vlo[u] = vtr(vb + vaddr[0] + u * 512); vhi[u] = vtr(vb + vaddr[1] + u * 512); } }
;     if (HAS_QK) { const int ad = C1 ? sub1(kaddr[0]) : kaddr[0]; ka = *(const ATT_LAS bf16x8*)(kb + ad); qa = *(const ATT_LAS bf16x8*)(qb_ + ad);
; #pragma unroll
;         for (int i = 0; i < 16; ++i) Snext[i] = 0.f; }
;     float sa = 0.f, sb = 0.f;
; #pragma unroll
;     for (int g = 0; g < 4; ++g) {
;         s16x4 nlo[2], nhi[2]; bf16x8 nk, nq;
;         if (g < 3) {
;             if (HAS_PV) {
; #pragma unroll
;                 for (int u = 0; u < 2; ++u) { const int off = (2 * ((g + 1) & 1) + u) * 512 + ((g + 1) >> 1) * 4096; nlo[u] = vtr(vb + vaddr[0] + off); nhi[u] = vtr(vb + vaddr[1] + off); } }
;             if (HAS_QK) { const int ad = C1 ? sub1(kaddr[g + 1]) : kaddr[g + 1]; nk = *(const ATT_LAS bf16x8*)(kb + ad); nq = *(const ATT_LAS bf16x8*)(qb_ + ad); }
;         }
;         if (HAS_PV) { const bf16x8 pa = __builtin_bit_cast(bf16x8, pkin[g >> 1]);
; #pragma unroll
;             for (int u = 0; u < 2; ++u) { const bf16x8 vf = __builtin_shufflevector(vlo[u], vhi[u], 0, 1, 2, 3, 4, 5, 6, 7); Opv[2 * (g & 1) + u] = ATT_MFMA(pa, vf, Opv[2 * (g & 1) + u]); } }
;         if (HAS_QK) Snext = ATT_MFMA(ka, qa, Snext);
; #pragma unroll
;         for (int e = 4 * g; e < 4 * g + 4; e += 2) { Scur[e] = __builtin_amdgcn_exp2f(Scur[e] - m); Scur[e + 1] = __builtin_amdgcn_exp2f(Scur[e + 1] - m); sa += Scur[e]; sb += Scur[e + 1]; }
;         if (g & 1) pkout[g >> 1] = (u32x4){cvtpk(Scur[4 * g - 4], Scur[4 * g - 3]), cvtpk(Scur[4 * g - 2], Scur[4 * g - 1]), cvtpk(Scur[4 * g], Scur[4 * g + 1]), cvtpk(Scur[4 * g + 2], Scur[4 * g + 3])};
;         if (g < 3) {
;             if (HAS_PV) {
; #pragma unroll
;                 for (int u = 0; u < 2; ++u) { vlo[u] = nlo[u]; vhi[u] = nhi[u]; } }
;             if (HAS_QK) { ka = nk; qa = nq; }
;         }
;         __builtin_amdgcn_sched_barrier(0);
;     }
;     l += sa + sb;
;     return sa + sb;
; }
; __device__ __forceinline__ void pv_issue(f32x16 (&O)[4], const u32x4 (&pk)[2], const ATT_LAS unsigned char* vb, const int (&vaddr)[2]) {
; #pragma unroll
;     for (int s_ = 0; s_ < 2; ++s_) { const bf16x8 pa = __builtin_bit_cast(bf16x8, pk[s_]);
; #pragma unroll
.Lns_341_p1:
	ds_read_b64_tr_b16 v[8:9], v213 offset:59392
	ds_read_b64_tr_b16 v[6:7], v207 offset:57344
	ds_read_b64_tr_b16 v[146:147], v207 offset:57856
	ds_read_b64_tr_b16 v[150:151], v207 offset:58368
	ds_read_b64_tr_b16 v[154:155], v207 offset:58880
	ds_read_b64_tr_b16 v[148:149], v213 offset:59904
	ds_read_b64_tr_b16 v[152:153], v213 offset:60416
	ds_read_b64_tr_b16 v[156:157], v213 offset:60928
	s_waitcnt lgkmcnt(1)
	v_mfma_f32_32x32x16_bf16 v[34:49], v[2:5], v[6:9], v[34:49]
	v_exp_f32_e32 v15, v162
	v_exp_f32_e32 v14, v163
	v_exp_f32_e32 v163, v164
	v_mfma_f32_32x32x16_bf16 v[50:65], v[2:5], v[146:149], v[50:65]
	v_exp_f32_e32 v162, v165
	v_mfma_f32_32x32x16_bf16 v[66:81], v[2:5], v[150:153], v[66:81]
	ds_read_b64_tr_b16 v[146:147], v207 offset:61440
	ds_read_b64_tr_b16 v[148:149], v213 offset:63488
	ds_read_b64_tr_b16 v[160:161], v213 offset:64000
	ds_read_b64_tr_b16 v[158:159], v207 offset:61952
	v_exp_f32_e32 v165, v166
	v_exp_f32_e32 v164, v167
	v_exp_f32_e32 v167, v168
	s_waitcnt lgkmcnt(2)
	v_mfma_f32_32x32x16_bf16 v[82:97], v[2:5], v[154:157], v[82:97]
	v_exp_f32_e32 v166, v169
	v_cvt_pk_bf16_f32 v6, v15, v14
	v_cvt_pk_bf16_f32 v7, v163, v162
	v_cvt_pk_bf16_f32 v8, v165, v164
	v_cvt_pk_bf16_f32 v9, v167, v166
	v_mfma_f32_32x32x16_bf16 v[34:49], v[10:13], v[146:149], v[34:49]
	ds_read_b64_tr_b16 v[2:3], v207 offset:62464
	ds_read_b64_tr_b16 v[4:5], v213 offset:64512
	ds_read_b64_tr_b16 v[152:153], v213 offset:65024
	ds_read_b64_tr_b16 v[150:151], v207 offset:62976
	v_exp_f32_e32 v147, v170
	v_exp_f32_e32 v146, v171
	v_exp_f32_e32 v149, v172
	s_waitcnt lgkmcnt(0)
	v_mfma_f32_32x32x16_bf16 v[50:65], v[10:13], v[158:161], v[50:65]
	v_exp_f32_e32 v148, v173
	v_mfma_f32_32x32x16_bf16 v[66:81], v[10:13], v[2:5], v[66:81]
	v_exp_f32_e32 v155, v174
	v_exp_f32_e32 v154, v175
	v_exp_f32_e32 v157, v176
	v_mfma_f32_32x32x16_bf16 v[82:97], v[10:13], v[150:153], v[82:97]
	v_add_f32_e64 v10, v162, v14
	v_add_f32_e64 v11, v163, v15
	v_exp_f32_e32 v156, v177
	v_add_f32_e32 v10, v164, v10
	v_add_f32_e32 v11, v165, v11
	v_cvt_pk_bf16_f32 v2, v147, v146
	v_cvt_pk_bf16_f32 v3, v149, v148
	v_cvt_pk_bf16_f32 v4, v155, v154
	v_cvt_pk_bf16_f32 v5, v157, v156
	v_add_f32_e32 v10, v166, v10
	v_add_f32_e32 v11, v167, v11
	v_add_f32_e32 v10, v146, v10
	v_add_f32_e32 v11, v147, v11
	v_add_f32_e32 v10, v148, v10
	v_add_f32_e32 v11, v149, v11
	v_add_f32_e32 v10, v154, v10
	v_add_f32_e32 v11, v155, v11
	v_add_f32_e32 v10, v156, v10
	v_add_f32_e32 v11, v157, v11
	v_add_f32_e32 v10, v10, v11
	v_cmp_nge_f32_e32 vcc, s58, v10
	s_cbranch_vccnz .Lfix_slow_4
	v_add_f32_e32 v224, v181, v10
	ds_read_b64_tr_b16 v[12:13], v213 offset:59392
	ds_read_b64_tr_b16 v[10:11], v207 offset:57344
	ds_read_b64_tr_b16 v[146:147], v207 offset:57856
	ds_read_b64_tr_b16 v[150:151], v207 offset:58368
	ds_read_b64_tr_b16 v[154:155], v207 offset:58880
	ds_read_b64_tr_b16 v[148:149], v213 offset:59904
	ds_read_b64_tr_b16 v[152:153], v213 offset:60416
	ds_read_b64_tr_b16 v[156:157], v213 offset:60928
	ds_read_b64_tr_b16 v[160:161], v213 offset:63488
	ds_read_b64_tr_b16 v[158:159], v207 offset:61440
	ds_read_b64_tr_b16 v[162:163], v207 offset:61952
	ds_read_b64_tr_b16 v[166:167], v207 offset:62464
	ds_read_b64_tr_b16 v[170:171], v207 offset:62976
	ds_read_b64_tr_b16 v[164:165], v213 offset:64000
	ds_read_b64_tr_b16 v[168:169], v213 offset:64512
	s_waitcnt lgkmcnt(7)
	v_mfma_f32_32x32x16_bf16 v[130:145], v[6:9], v[10:13], v[130:145]
	v_mfma_f32_32x32x16_bf16 v[114:129], v[6:9], v[146:149], v[114:129]
	v_mfma_f32_32x32x16_bf16 v[98:113], v[6:9], v[150:153], v[98:113]
	v_mfma_f32_32x32x16_bf16 v[18:33], v[6:9], v[154:157], v[18:33]
	ds_read_b64_tr_b16 v[172:173], v213 offset:65024
	s_waitcnt lgkmcnt(0)
	v_mfma_f32_32x32x16_bf16 v[130:145], v[2:5], v[158:161], v[130:145]
	v_mfma_f32_32x32x16_bf16 v[114:129], v[2:5], v[162:165], v[114:129]
	v_mfma_f32_32x32x16_bf16 v[98:113], v[2:5], v[166:169], v[98:113]
	v_mfma_f32_32x32x16_bf16 v[18:33], v[2:5], v[170:173], v[18:33]
	s_add_i32 s80, s80, 64
	s_add_u32 s94, s94, 0x20000
	s_addc_u32 s95, s95, 0
	s_waitcnt vmcnt(0)
	s_add_u32 s92, s92, 0x20000
	s_addc_u32 s93, s93, 0
	s_cmp_eq_u32 s76, s79
	v_subrev_u32_e32 v214, 64, v214
	s_barrier
	s_cbranch_scc0 .LBB0_289
	s_branch .LBB0_352

; #define ATT_LAS __attribute__((address_space(3)))
; template <bool C1> __device__ __forceinline__ void slow_step(bool MASK, f32x16& S, const ATT_LAS unsigned char* kb, const ATT_LAS unsigned char* qbase, const int (&kaddr)[4], const int (&vaddr)[2], ...
;     l = l_saved;
;     qk_issue<C1>(S, kb, qbase, kaddr);
;     rowmax_rescale(MASK, S, O, m, l, kvr, r, h, wsf);
;     f32x16 dummy;
;     step_fused<false, false, false>(S, m, l, pk, O, pk, kb, vaddr, dummy, kb, qbase, kaddr);
; }
.Lfix_slow_1:
	v_add_u32_e32 v216, s81, v203
	v_add_u32_e32 v218, s81, v204
	v_add_u32_e32 v220, s81, v205
	v_add_u32_e32 v222, s81, v206
	v_add_u32_e32 v248, s81, v209
	v_add_u32_e32 v249, s81, v210
	v_add_u32_e32 v250, s81, v211
	v_add_u32_e32 v251, s81, v212
	s_branch .Lslow_1
.Lfix_slow_2:
	v_add_u32_e32 v216, s81, v203
	v_add_u32_e32 v218, s81, v204
	v_add_u32_e32 v220, s81, v205
	v_add_u32_e32 v222, s81, v206
	v_add_u32_e32 v248, s81, v209
	v_add_u32_e32 v249, s81, v210
	v_add_u32_e32 v250, s81, v211
	v_add_u32_e32 v251, s81, v212
	v_add_u32_e32 v178, s81, v213
	v_add_u32_e32 v179, s81, v207
	s_branch .Lslow_2
